# accumulator clears interleaved into the scalar tile-mapping blocks at each GEMM tile head (overlap across the tile boundary)
# baseline (speedup 1.0000x reference)
;     __device__ bool next(int i, Unit& u) const { const int t = i / 3, b = i - 3 * t; if (!so.map((long)t * so.G + so.c, u)) return false; u.pn += 8 * b; return true; }
;     __device__ bool map(long L, Unit& u) const {
;         if (L >= nwg) return false;
;         int wgid = (int)L; { const int q = nwg / NXCD, r = nwg % NXCD, xcd = wgid % NXCD, off = wgid / NXCD; wgid = (xcd < r ? xcd * (q + 1) : r * (q + 1) + (xcd - r) * q) + off; }
;         const int nig = WGM * nN, gid = wgid / nig, fm = gid * WGM, gsz = (nM - fm) < WGM ? (nM - fm) : WGM;
;         u.pm = fm + ((wgid % nig) % gsz); u.pn = (wgid % nig) / gsz; return true;
;     }
;     __device__ bool next(int i, Unit& u) const { return map((long)i * G + c, u); }
; template <class Epi, class Sched, bool AREMAP>
; __device__ __forceinline__ void gemm_phase(LAS unsigned char* lds, const Gemm g, const Sched& S, const Epi& E, int wv) {
;     ...
; #pragma unroll
;         for (int a = 0; a < 2; ++a)
; #pragma unroll
;             for (int b = 0; b < 2; ++b)
; #pragma unroll
;                 for (int m = 0; m < 4; ++m)
; #pragma unroll
;                     for (int n = 0; n < 2; ++n) acc[a][b][m][n] = (f32x4){0.f, 0.f, 0.f, 0.f};
.LBB0_195:
	s_add_i32 s41, s41, 1
	s_mul_i32 s0, s41, s37
	s_mul_hi_u32 s1, s41, s23
	s_add_i32 s1, s1, s0
	v_mov_b64_e32 v[4:5], 0
	v_mov_b64_e32 v[6:7], 0
	v_mov_b64_e32 v[8:9], 0
	s_mul_i32 s0, s41, s23
	v_mov_b64_e32 v[10:11], 0
	v_mov_b64_e32 v[12:13], 0
	v_mov_b64_e32 v[14:15], 0
	s_add_u32 s12, s0, s24
	v_mov_b64_e32 v[16:17], 0
	v_mov_b64_e32 v[26:27], 0
	v_mov_b64_e32 v[28:29], 0
	s_addc_u32 s13, s1, s26
	v_mov_b64_e32 v[30:31], 0
	v_mov_b64_e32 v[32:33], 0
	v_mov_b64_e32 v[42:43], 0
	v_mov_b64_e32 v[2:3], 0xfff
	v_mov_b64_e32 v[44:45], 0
	v_mov_b64_e32 v[46:47], 0
	v_mov_b64_e32 v[48:49], 0
	v_cmp_gt_i64_e64 s[0:1], s[12:13], v[2:3]
	v_mov_b64_e32 v[18:19], 0
	v_mov_b64_e32 v[20:21], 0
	v_mov_b64_e32 v[22:23], 0
	s_and_b64 vcc, exec, s[0:1]
	v_mov_b64_e32 v[24:25], 0
	v_mov_b64_e32 v[34:35], 0
	v_mov_b64_e32 v[36:37], 0
	s_cbranch_vccnz .LBB0_201
	s_ashr_i32 s8, s12, 31
	s_lshr_b32 s8, s8, 29
	s_add_i32 s10, s12, s8
	s_and_b32 s8, s10, -8
	s_sub_i32 s11, s12, s8
	s_cmp_gt_i32 s11, -1
	s_mov_b64 s[8:9], -1
	s_cbranch_scc0 .LBB0_198
	s_lshl_b32 s14, s11, 9
	s_mov_b64 s[8:9], 0

;     __device__ bool next(int i, Unit& u) const { const int t = i / 3, b = i - 3 * t; if (!so.map((long)t * so.G + so.c, u)) return false; u.pn += 8 * b; return true; }
;     __device__ bool map(long L, Unit& u) const {
;         if (L >= nwg) return false;
;         int wgid = (int)L; { const int q = nwg / NXCD, r = nwg % NXCD, xcd = wgid % NXCD, off = wgid / NXCD; wgid = (xcd < r ? xcd * (q + 1) : r * (q + 1) + (xcd - r) * q) + off; }
;         const int nig = WGM * nN, gid = wgid / nig, fm = gid * WGM, gsz = (nM - fm) < WGM ? (nM - fm) : WGM;
;         u.pm = fm + ((wgid % nig) % gsz); u.pn = (wgid % nig) / gsz; return true;
;     }
;     __device__ bool next(int i, Unit& u) const { return map((long)i * G + c, u); }
; template <class Epi, class Sched, bool AREMAP>
; __device__ __forceinline__ void gemm_phase(LAS unsigned char* lds, const Gemm g, const Sched& S, const Epi& E, int wv) {
;     ...
; #pragma unroll
;         for (int a = 0; a < 2; ++a)
; #pragma unroll
;             for (int b = 0; b < 2; ++b)
; #pragma unroll
;                 for (int m = 0; m < 4; ++m)
; #pragma unroll
;                     for (int n = 0; n < 2; ++n) acc[a][b][m][n] = (f32x4){0.f, 0.f, 0.f, 0.f};
.LBB0_201:
	v_mov_b64_e32 v[2:3], 0x1000
	v_mov_b64_e32 v[38:39], 0
	v_mov_b64_e32 v[40:41], 0
	v_mov_b64_e32 v[50:51], 0
	s_ashr_i32 s11, s10, 31
	v_mov_b64_e32 v[52:53], 0
	v_mov_b64_e32 v[54:55], 0
	v_mov_b64_e32 v[56:57], 0
	v_cmp_lt_i64_e32 vcc, s[12:13], v[2:3]
	v_mov_b64_e32 v[58:59], 0
	v_mov_b64_e32 v[60:61], 0
	v_mov_b64_e32 v[62:63], 0
	s_lshl_b64 s[12:13], s[10:11], 20
	v_mov_b64_e32 v[64:65], 0
	v_mov_b64_e32 v[66:67], 0
	v_mov_b64_e32 v[68:69], 0
	s_add_u32 s12, s27, s12
	v_mov_b64_e32 v[70:71], 0
	v_mov_b64_e32 v[72:73], 0
	v_mov_b64_e32 v[74:75], 0
	s_addc_u32 s13, s28, s13
	v_mov_b64_e32 v[76:77], 0
	v_mov_b64_e32 v[78:79], 0
	v_mov_b64_e32 v[80:81], 0
	s_and_b64 s[14:15], vcc, exec
	v_mov_b64_e32 v[90:91], 0
	v_mov_b64_e32 v[92:93], 0
	v_mov_b64_e32 v[94:95], 0
	s_cselect_b32 s11, s13, s19
	v_mov_b64_e32 v[96:97], 0
	v_mov_b64_e32 v[106:107], 0
	v_mov_b64_e32 v[108:109], 0
	s_cselect_b32 s47, s12, s18
	v_mov_b64_e32 v[110:111], 0
	v_mov_b64_e32 v[112:113], 0
	v_mov_b64_e32 v[82:83], 0
	s_ashr_i32 s9, s8, 31
	v_mov_b64_e32 v[84:85], 0
	v_mov_b64_e32 v[86:87], 0
	v_mov_b64_e32 v[88:89], 0
	s_lshl_b64 s[14:15], s[8:9], 20
	v_mov_b64_e32 v[98:99], 0
	v_mov_b64_e32 v[100:101], 0
	v_mov_b64_e32 v[102:103], 0
	s_add_u32 s14, s2, s14
	v_mov_b64_e32 v[104:105], 0
	v_mov_b64_e32 v[114:115], 0
	v_mov_b64_e32 v[116:117], 0
	s_addc_u32 s15, s3, s15
	v_mov_b64_e32 v[118:119], 0
	v_mov_b64_e32 v[120:121], 0
	v_mov_b64_e32 v[122:123], 0
	s_and_b64 s[20:21], vcc, exec
	v_mov_b64_e32 v[124:125], 0
	v_mov_b64_e32 v[126:127], 0
	v_mov_b64_e32 v[128:129], 0
	s_cselect_b32 s9, s15, s17
	s_cselect_b32 s52, s14, s16
	s_add_u32 s53, s16, 0x100
	s_addc_u32 s55, s17, 0
	s_add_u32 s16, s18, 0x80080
	v_mov_b64_e32 v[2:3], 0
	s_addc_u32 s17, s19, 0
	s_mov_b32 s56, -2

;     __device__ bool next(int i, Unit& u) const { const int t = i / 3, b = i - 3 * t; if (!so.map((long)t * so.G + so.c, u)) return false; u.pn += 8 * b; return true; }
;     __device__ bool map(long L, Unit& u) const {
;         if (L >= nwg) return false;
;         int wgid = (int)L; { const int q = nwg / NXCD, r = nwg % NXCD, xcd = wgid % NXCD, off = wgid / NXCD; wgid = (xcd < r ? xcd * (q + 1) : r * (q + 1) + (xcd - r) * q) + off; }
;         const int nig = WGM * nN, gid = wgid / nig, fm = gid * WGM, gsz = (nM - fm) < WGM ? (nM - fm) : WGM;
;         u.pm = fm + ((wgid % nig) % gsz); u.pn = (wgid % nig) / gsz; return true;
;     }
;     __device__ bool next(int i, Unit& u) const { return map((long)i * G + c, u); }
; template <class Epi, class Sched, bool AREMAP>
; __device__ __forceinline__ void gemm_phase(LAS unsigned char* lds, const Gemm g, const Sched& S, const Epi& E, int wv) {
;     ...
; #pragma unroll
;         for (int a = 0; a < 2; ++a)
; #pragma unroll
;             for (int b = 0; b < 2; ++b)
; #pragma unroll
;                 for (int m = 0; m < 4; ++m)
; #pragma unroll
;                     for (int n = 0; n < 2; ++n) acc[a][b][m][n] = (f32x4){0.f, 0.f, 0.f, 0.f};
.LBB0_392:
	s_add_i32 s41, s41, 1
	s_mul_i32 s0, s41, s37
	s_mul_hi_u32 s1, s41, s18
	s_add_i32 s1, s1, s0
	v_mov_b64_e32 v[4:5], 0
	v_mov_b64_e32 v[6:7], 0
	v_mov_b64_e32 v[8:9], 0
	v_mov_b64_e32 v[10:11], 0
	s_mul_i32 s0, s41, s18
	v_mov_b64_e32 v[12:13], 0
	v_mov_b64_e32 v[14:15], 0
	v_mov_b64_e32 v[16:17], 0
	v_mov_b64_e32 v[26:27], 0
	s_add_u32 s10, s0, s19
	v_mov_b64_e32 v[28:29], 0
	v_mov_b64_e32 v[30:31], 0
	v_mov_b64_e32 v[32:33], 0
	v_mov_b64_e32 v[42:43], 0
	s_addc_u32 s11, s1, s27
	v_mov_b64_e32 v[44:45], 0
	v_mov_b64_e32 v[46:47], 0
	v_mov_b64_e32 v[48:49], 0
	v_mov_b64_e32 v[18:19], 0
	v_mov_b64_e32 v[2:3], 0xc00
	v_mov_b64_e32 v[20:21], 0
	v_mov_b64_e32 v[22:23], 0
	v_mov_b64_e32 v[24:25], 0
	v_mov_b64_e32 v[34:35], 0
	v_cmp_lt_i64_e64 s[2:3], s[10:11], v[2:3]
	v_mov_b64_e32 v[36:37], 0
	v_mov_b64_e32 v[38:39], 0
	v_mov_b64_e32 v[40:41], 0
	v_mov_b64_e32 v[50:51], 0
	v_mov_b64_e32 v[2:3], 0xbff
	v_mov_b64_e32 v[52:53], 0
	v_mov_b64_e32 v[54:55], 0
	v_mov_b64_e32 v[56:57], 0
	v_mov_b64_e32 v[58:59], 0
	v_cmp_gt_i64_e64 s[0:1], s[10:11], v[2:3]
	v_mov_b64_e32 v[60:61], 0
	v_mov_b64_e32 v[62:63], 0
	v_mov_b64_e32 v[64:65], 0
	v_mov_b64_e32 v[66:67], 0
	s_and_b64 vcc, exec, s[0:1]
	v_mov_b64_e32 v[68:69], 0
	v_mov_b64_e32 v[70:71], 0
	v_mov_b64_e32 v[72:73], 0
	v_mov_b64_e32 v[74:75], 0
	s_cbranch_vccnz .LBB0_394
	s_ashr_i32 s6, s10, 31
	s_lshr_b32 s6, s6, 29
	s_add_i32 s6, s10, s6
	s_ashr_i32 s7, s6, 3
	s_and_b32 s6, s6, -8
	s_sub_i32 s6, s10, s6
	s_cmp_lt_i32 s6, 0
	s_cselect_b32 s8, s33, 0x180
	s_mul_i32 s6, s8, s6
	s_add_i32 s6, s6, s7
	s_mul_hi_i32 s7, s6, 0x2aaaaaab
	s_lshr_b32 s8, s7, 31
	s_ashr_i32 s7, s7, 4
	s_add_i32 s7, s7, s8
	s_lshl_b32 s8, s7, 2
	s_sub_i32 s9, 0x80, s8
	s_min_i32 s9, s9, 4
	s_abs_i32 s10, s9
	v_cvt_f32_u32_e32 v2, s10
	s_sub_i32 s12, 0, s10
	s_mulk_i32 s7, 0x60
	s_sub_i32 s7, s6, s7
	v_rcp_iflag_f32_e32 v2, v2
	s_abs_i32 s6, s7
	s_xor_b32 s11, s7, s9
	s_ashr_i32 s11, s11, 31
	v_mul_f32_e32 v2, 0x4f7ffffe, v2
	v_cvt_u32_f32_e32 v2, v2
	s_nop 0
	v_readfirstlane_b32 s13, v2
	s_mul_i32 s12, s12, s13
	s_mul_hi_u32 s12, s13, s12
	s_add_i32 s13, s13, s12
	s_mul_hi_u32 s12, s6, s13
	s_mul_i32 s13, s12, s10
	s_sub_i32 s6, s6, s13
	s_add_i32 s38, s12, 1
	s_sub_i32 s13, s6, s10
	s_cmp_ge_u32 s6, s10
	s_cselect_b32 s12, s38, s12
	s_cselect_b32 s6, s13, s6
	s_add_i32 s13, s12, 1
	s_cmp_ge_u32 s6, s10
	s_cselect_b32 s6, s13, s12
	s_xor_b32 s6, s6, s11
	s_sub_i32 s6, s6, s11
	s_mul_i32 s9, s6, s9
	s_sub_i32 s7, s7, s9
	s_add_i32 s8, s7, s8

; template <class Epi, class Sched, bool AREMAP>
; __device__ __forceinline__ void gemm_phase(LAS unsigned char* lds, const Gemm g, const Sched& S, const Epi& E, int wv) {
;     ...
;         const char* nA = has_next ? PG8_UA(nxt) : cA; const char* nB = has_next ? PG8_UB(nxt) : cB;
;         for (int t = 0; t < nt; t += 2) {
;             const bool last = (t == nt - 2);
;             const char* a1 = cA + (size_t)(t + 1) * kstep;
;             const char* a2 = last ? nA : cA + (size_t)(t + 2) * kstep; const char* b2 = last ? nB : cB + (size_t)(t + 2) * kstep;
;     ...
; #pragma unroll
;         for (int a = 0; a < 2; ++a)
; #pragma unroll
;             for (int b = 0; b < 2; ++b)
; #pragma unroll
;                 for (int m = 0; m < 4; ++m)
; #pragma unroll
;                     for (int n = 0; n < 2; ++n) acc[a][b][m][n] = (f32x4){0.f, 0.f, 0.f, 0.f};
.LBB0_396:
	s_ashr_i32 s7, s6, 31
	v_mov_b64_e32 v[76:77], 0
	v_mov_b64_e32 v[78:79], 0
	v_mov_b64_e32 v[80:81], 0
	v_mov_b64_e32 v[90:91], 0
	s_lshl_b64 s[12:13], s[6:7], 19
	v_mov_b64_e32 v[92:93], 0
	v_mov_b64_e32 v[94:95], 0
	v_mov_b64_e32 v[96:97], 0
	v_mov_b64_e32 v[106:107], 0
	s_add_u32 s12, s23, s12
	v_mov_b64_e32 v[108:109], 0
	v_mov_b64_e32 v[110:111], 0
	v_mov_b64_e32 v[112:113], 0
	v_mov_b64_e32 v[82:83], 0
	s_addc_u32 s13, s25, s13
	v_mov_b64_e32 v[84:85], 0
	v_mov_b64_e32 v[86:87], 0
	v_mov_b64_e32 v[88:89], 0
	v_mov_b64_e32 v[98:99], 0
	s_and_b64 s[2:3], s[2:3], exec
	v_mov_b64_e32 v[100:101], 0
	v_mov_b64_e32 v[102:103], 0
	v_mov_b64_e32 v[104:105], 0
	v_mov_b64_e32 v[114:115], 0
	s_cselect_b32 s7, s13, s15
	v_mov_b64_e32 v[116:117], 0
	v_mov_b64_e32 v[118:119], 0
	v_mov_b64_e32 v[120:121], 0
	v_mov_b64_e32 v[122:123], 0
	s_cselect_b32 s9, s12, s14
	v_mov_b64_e32 v[124:125], 0
	v_mov_b64_e32 v[126:127], 0
	v_mov_b64_e32 v[128:129], 0
	s_add_u32 s47, s14, 0x100
	s_addc_u32 s52, s15, 0
	s_add_u32 s2, s16, 0x40080
	v_mov_b64_e32 v[2:3], 0
	s_addc_u32 s3, s17, 0
	s_mov_b32 s53, -2

;     __device__ bool next(int i, Unit& u) const { const int t = i / 3, b = i - 3 * t; if (!so.map((long)t * so.G + so.c, u)) return false; u.pn += 8 * b; return true; }
;     __device__ bool map(long L, Unit& u) const {
;         if (L >= nwg) return false;
;         int wgid = (int)L; { const int q = nwg / NXCD, r = nwg % NXCD, xcd = wgid % NXCD, off = wgid / NXCD; wgid = (xcd < r ? xcd * (q + 1) : r * (q + 1) + (xcd - r) * q) + off; }
;         const int nig = WGM * nN, gid = wgid / nig, fm = gid * WGM, gsz = (nM - fm) < WGM ? (nM - fm) : WGM;
;         u.pm = fm + ((wgid % nig) % gsz); u.pn = (wgid % nig) / gsz; return true;
;     }
;     __device__ bool next(int i, Unit& u) const { return map((long)i * G + c, u); }
;     __device__ void init(int M, int N, int G_, int c_) { so.init(M, N, G_, c_); }
; template <class Epi, class Sched, bool AREMAP>
; __device__ __forceinline__ void gemm_phase(LAS unsigned char* lds, const Gemm g, const Sched& S, const Epi& E, int wv) {
;     ...
; #pragma unroll
;         for (int a = 0; a < 2; ++a)
; #pragma unroll
;             for (int b = 0; b < 2; ++b)
; #pragma unroll
;                 for (int m = 0; m < 4; ++m)
; #pragma unroll
;                     for (int n = 0; n < 2; ++n) acc[a][b][m][n] = (f32x4){0.f, 0.f, 0.f, 0.f};
.LBB0_419:
	s_add_i32 s65, s65, 1
	s_mul_hi_u32 s0, s65, 0xaaaaaaab
	s_lshr_b32 s3, s0, 1
	s_mul_i32 s1, s3, s25
	v_mov_b64_e32 v[4:5], 0
	v_mov_b64_e32 v[6:7], 0
	v_mov_b64_e32 v[8:9], 0
	s_mul_hi_i32 s0, s3, s25
	v_mov_b64_e32 v[18:19], 0
	v_mov_b64_e32 v[20:21], 0
	v_mov_b64_e32 v[22:23], 0
	s_add_u32 s14, s1, s26
	v_mov_b64_e32 v[24:25], 0
	v_mov_b64_e32 v[34:35], 0
	v_mov_b64_e32 v[36:37], 0
	s_addc_u32 s15, s0, s63
	v_mov_b64_e32 v[38:39], 0
	v_mov_b64_e32 v[40:41], 0
	v_mov_b64_e32 v[50:51], 0
	v_cmp_gt_i64_e64 s[0:1], s[14:15], v[188:189]
	v_mov_b64_e32 v[52:53], 0
	v_mov_b64_e32 v[54:55], 0
	v_mov_b64_e32 v[56:57], 0
	s_and_b64 vcc, exec, s[0:1]
	v_mov_b64_e32 v[10:11], 0
	v_mov_b64_e32 v[12:13], 0
	v_mov_b64_e32 v[14:15], 0
	s_cbranch_vccnz .LBB0_425
	s_ashr_i32 s5, s14, 31
	s_lshr_b32 s5, s5, 29
	s_add_i32 s5, s14, s5
	s_and_b32 s10, s5, -8
	s_sub_i32 s12, s14, s10
	s_cmp_gt_i32 s12, -1
	s_mov_b64 s[10:11], -1
	s_cbranch_scc0 .LBB0_422
	s_lshl_b32 s13, s12, 7
	s_mov_b64 s[10:11], 0

;     __device__ bool next(int i, Unit& u) const { const int t = i / 3, b = i - 3 * t; if (!so.map((long)t * so.G + so.c, u)) return false; u.pn += 8 * b; return true; }
;     __device__ bool map(long L, Unit& u) const {
;         if (L >= nwg) return false;
;         int wgid = (int)L; { const int q = nwg / NXCD, r = nwg % NXCD, xcd = wgid % NXCD, off = wgid / NXCD; wgid = (xcd < r ? xcd * (q + 1) : r * (q + 1) + (xcd - r) * q) + off; }
;         const int nig = WGM * nN, gid = wgid / nig, fm = gid * WGM, gsz = (nM - fm) < WGM ? (nM - fm) : WGM;
;         u.pm = fm + ((wgid % nig) % gsz); u.pn = (wgid % nig) / gsz; return true;
;     }
;     __device__ bool next(int i, Unit& u) const { return map((long)i * G + c, u); }
;     __device__ void init(int M, int N, int G_, int c_) { so.init(M, N, G_, c_); }
; template <class Epi, class Sched, bool AREMAP>
; __device__ __forceinline__ void gemm_phase(LAS unsigned char* lds, const Gemm g, const Sched& S, const Epi& E, int wv) {
;     ...
; #pragma unroll
;         for (int a = 0; a < 2; ++a)
; #pragma unroll
;             for (int b = 0; b < 2; ++b)
; #pragma unroll
;                 for (int m = 0; m < 4; ++m)
; #pragma unroll
;                     for (int n = 0; n < 2; ++n) acc[a][b][m][n] = (f32x4){0.f, 0.f, 0.f, 0.f};
.LBB0_425:
	s_ashr_i32 s11, s10, 31
	v_mov_b64_e32 v[16:17], 0
	v_mov_b64_e32 v[26:27], 0
	v_mov_b64_e32 v[28:29], 0
	v_cmp_lt_i64_e32 vcc, s[14:15], v[190:191]
	v_mov_b64_e32 v[30:31], 0
	v_mov_b64_e32 v[32:33], 0
	v_mov_b64_e32 v[42:43], 0
	s_lshl_b64 s[14:15], s[10:11], 20
	v_mov_b64_e32 v[44:45], 0
	v_mov_b64_e32 v[46:47], 0
	v_mov_b64_e32 v[48:49], 0
	s_add_u32 s14, s28, s14
	v_mov_b64_e32 v[58:59], 0
	v_mov_b64_e32 v[60:61], 0
	v_mov_b64_e32 v[62:63], 0
	s_addc_u32 s15, s29, s15
	v_mov_b64_e32 v[64:65], 0
	v_mov_b64_e32 v[66:67], 0
	v_mov_b64_e32 v[68:69], 0
	s_and_b64 s[16:17], vcc, exec
	v_mov_b64_e32 v[70:71], 0
	v_mov_b64_e32 v[72:73], 0
	v_mov_b64_e32 v[82:83], 0
	s_cselect_b32 s3, s15, s21
	v_mov_b64_e32 v[84:85], 0
	v_mov_b64_e32 v[86:87], 0
	v_mov_b64_e32 v[88:89], 0
	s_cselect_b32 s5, s14, s20
	v_mov_b64_e32 v[98:99], 0
	v_mov_b64_e32 v[100:101], 0
	v_mov_b64_e32 v[102:103], 0
	s_ashr_i32 s13, s12, 31
	v_mov_b64_e32 v[104:105], 0
	v_mov_b64_e32 v[114:115], 0
	v_mov_b64_e32 v[116:117], 0
	s_lshl_b64 s[16:17], s[12:13], 20
	v_mov_b64_e32 v[118:119], 0
	v_mov_b64_e32 v[120:121], 0
	v_mov_b64_e32 v[74:75], 0
	s_add_u32 s16, s30, s16
	v_mov_b64_e32 v[76:77], 0
	v_mov_b64_e32 v[78:79], 0
	v_mov_b64_e32 v[80:81], 0
	s_addc_u32 s17, s31, s17
	v_mov_b64_e32 v[90:91], 0
	v_mov_b64_e32 v[92:93], 0
	v_mov_b64_e32 v[94:95], 0
	s_and_b64 s[22:23], vcc, exec
	v_mov_b64_e32 v[96:97], 0
	v_mov_b64_e32 v[106:107], 0
	v_mov_b64_e32 v[108:109], 0
	s_cselect_b32 s11, s17, s19
	v_mov_b64_e32 v[110:111], 0
	v_mov_b64_e32 v[112:113], 0
	v_mov_b64_e32 v[122:123], 0
	s_cselect_b32 s13, s16, s18
	v_mov_b64_e32 v[124:125], 0
	v_mov_b64_e32 v[126:127], 0
	v_mov_b64_e32 v[128:129], 0
	s_add_u32 s36, s18, 0x100
	s_addc_u32 s37, s19, 0
	s_add_u32 s18, s20, 0x80080
	v_mov_b64_e32 v[2:3], 0
	s_addc_u32 s19, s21, 0
	s_mov_b32 s46, -2

;     __device__ bool next(int i, Unit& u) const { const int t = i / 3, b = i - 3 * t; if (!so.map((long)t * so.G + so.c, u)) return false; u.pn += 8 * b; return true; }
;     __device__ bool map(long L, Unit& u) const {
;         if (L >= nwg) return false;
;         int wgid = (int)L; { const int q = nwg / NXCD, r = nwg % NXCD, xcd = wgid % NXCD, off = wgid / NXCD; wgid = (xcd < r ? xcd * (q + 1) : r * (q + 1) + (xcd - r) * q) + off; }
;         const int nig = WGM * nN, gid = wgid / nig, fm = gid * WGM, gsz = (nM - fm) < WGM ? (nM - fm) : WGM;
;         u.pm = fm + ((wgid % nig) % gsz); u.pn = (wgid % nig) / gsz; return true;
;     }
;     __device__ bool next(int i, Unit& u) const { return map((long)i * G + c, u); }
; template <class Epi, class Sched, bool AREMAP>
; __device__ __forceinline__ void gemm_phase(LAS unsigned char* lds, const Gemm g, const Sched& S, const Epi& E, int wv) {
;     ...
; #pragma unroll
;         for (int a = 0; a < 2; ++a)
; #pragma unroll
;             for (int b = 0; b < 2; ++b)
; #pragma unroll
;                 for (int m = 0; m < 4; ++m)
; #pragma unroll
;                     for (int n = 0; n < 2; ++n) acc[a][b][m][n] = (f32x4){0.f, 0.f, 0.f, 0.f};
.LBB0_545:
	s_add_i32 s70, s70, 1
	s_mul_i32 s0, s70, s68
	s_mul_hi_u32 s1, s70, s11
	s_add_i32 s1, s1, s0
	v_mov_b64_e32 v[4:5], 0
	v_mov_b64_e32 v[18:19], 0
	v_mov_b64_e32 v[20:21], 0
	s_mul_i32 s0, s70, s11
	v_mov_b64_e32 v[6:7], 0
	v_mov_b64_e32 v[8:9], 0
	v_mov_b64_e32 v[22:23], 0
	s_add_u32 s24, s0, s36
	v_mov_b64_e32 v[24:25], 0
	v_mov_b64_e32 v[10:11], 0
	v_mov_b64_e32 v[12:13], 0
	s_addc_u32 s25, s1, s69
	v_mov_b64_e32 v[26:27], 0
	v_mov_b64_e32 v[28:29], 0
	v_mov_b64_e32 v[14:15], 0
	v_cmp_gt_i64_e64 s[0:1], s[24:25], v[188:189]
	v_mov_b64_e32 v[16:17], 0
	v_mov_b64_e32 v[30:31], 0
	v_mov_b64_e32 v[32:33], 0
	s_and_b64 vcc, exec, s[0:1]
	v_mov_b64_e32 v[34:35], 0
	v_mov_b64_e32 v[36:37], 0
	v_mov_b64_e32 v[50:51], 0
	s_cbranch_vccnz .LBB0_551
	s_ashr_i32 s20, s24, 31
	s_lshr_b32 s20, s20, 29
	s_add_i32 s22, s24, s20
	s_and_b32 s20, s22, -8
	s_sub_i32 s23, s24, s20
	s_cmp_gt_i32 s23, -1
	s_mov_b64 s[20:21], -1
	s_cbranch_scc0 .LBB0_548
	s_lshl_b32 s26, s23, 7
	s_mov_b64 s[20:21], 0

;     __device__ bool next(int i, Unit& u) const { const int t = i / 3, b = i - 3 * t; if (!so.map((long)t * so.G + so.c, u)) return false; u.pn += 8 * b; return true; }
;     __device__ bool map(long L, Unit& u) const {
;         if (L >= nwg) return false;
;         int wgid = (int)L; { const int q = nwg / NXCD, r = nwg % NXCD, xcd = wgid % NXCD, off = wgid / NXCD; wgid = (xcd < r ? xcd * (q + 1) : r * (q + 1) + (xcd - r) * q) + off; }
;         const int nig = WGM * nN, gid = wgid / nig, fm = gid * WGM, gsz = (nM - fm) < WGM ? (nM - fm) : WGM;
;         u.pm = fm + ((wgid % nig) % gsz); u.pn = (wgid % nig) / gsz; return true;
;     }
;     __device__ bool next(int i, Unit& u) const { return map((long)i * G + c, u); }
; template <class Epi, class Sched, bool AREMAP>
; __device__ __forceinline__ void gemm_phase(LAS unsigned char* lds, const Gemm g, const Sched& S, const Epi& E, int wv) {
;     ...
; #pragma unroll
;         for (int a = 0; a < 2; ++a)
; #pragma unroll
;             for (int b = 0; b < 2; ++b)
; #pragma unroll
;                 for (int m = 0; m < 4; ++m)
; #pragma unroll
;                     for (int n = 0; n < 2; ++n) acc[a][b][m][n] = (f32x4){0.f, 0.f, 0.f, 0.f};
.LBB0_551:
	s_ashr_i32 s23, s22, 31
	v_mov_b64_e32 v[52:53], 0
	v_mov_b64_e32 v[38:39], 0
	v_mov_b64_e32 v[40:41], 0
	v_cmp_lt_i64_e32 vcc, s[24:25], v[190:191]
	v_mov_b64_e32 v[54:55], 0
	v_mov_b64_e32 v[56:57], 0
	v_mov_b64_e32 v[42:43], 0
	s_lshl_b64 s[24:25], s[22:23], 20
	v_mov_b64_e32 v[44:45], 0
	v_mov_b64_e32 v[58:59], 0
	v_mov_b64_e32 v[60:61], 0
	s_add_u32 s24, s41, s24
	v_mov_b64_e32 v[46:47], 0
	v_mov_b64_e32 v[48:49], 0
	v_mov_b64_e32 v[62:63], 0
	s_addc_u32 s25, s46, s25
	v_mov_b64_e32 v[64:65], 0
	v_mov_b64_e32 v[66:67], 0
	v_mov_b64_e32 v[68:69], 0
	s_and_b64 s[26:27], vcc, exec
	v_mov_b64_e32 v[82:83], 0
	v_mov_b64_e32 v[84:85], 0
	v_mov_b64_e32 v[70:71], 0
	s_cselect_b32 s23, s25, s3
	v_mov_b64_e32 v[72:73], 0
	v_mov_b64_e32 v[86:87], 0
	v_mov_b64_e32 v[88:89], 0
	s_cselect_b32 s72, s24, s2
	v_mov_b64_e32 v[74:75], 0
	v_mov_b64_e32 v[76:77], 0
	v_mov_b64_e32 v[90:91], 0
	s_ashr_i32 s21, s20, 31
	v_mov_b64_e32 v[92:93], 0
	v_mov_b64_e32 v[78:79], 0
	v_mov_b64_e32 v[80:81], 0
	s_lshl_b64 s[26:27], s[20:21], 20
	v_mov_b64_e32 v[94:95], 0
	v_mov_b64_e32 v[96:97], 0
	v_mov_b64_e32 v[98:99], 0
	s_add_u32 s26, s47, s26
	v_mov_b64_e32 v[100:101], 0
	v_mov_b64_e32 v[114:115], 0
	v_mov_b64_e32 v[116:117], 0
	s_addc_u32 s27, s52, s27
	v_mov_b64_e32 v[102:103], 0
	v_mov_b64_e32 v[104:105], 0
	v_mov_b64_e32 v[118:119], 0
	s_and_b64 s[62:63], vcc, exec
	v_mov_b64_e32 v[120:121], 0
	v_mov_b64_e32 v[106:107], 0
	v_mov_b64_e32 v[108:109], 0
	s_cselect_b32 s21, s27, s35
	v_mov_b64_e32 v[122:123], 0
	v_mov_b64_e32 v[124:125], 0
	v_mov_b64_e32 v[110:111], 0
	s_cselect_b32 s73, s26, s34
	v_mov_b64_e32 v[112:113], 0
	v_mov_b64_e32 v[126:127], 0
	v_mov_b64_e32 v[128:129], 0
	s_add_u32 s74, s34, 0x100
	v_mov_b64_e32 v[2:3], 0
	s_addc_u32 s75, s35, 0
	s_mov_b32 s76, -2

;     __device__ bool next(int i, Unit& u) const { const int t = i / 3, b = i - 3 * t; if (!so.map((long)t * so.G + so.c, u)) return false; u.pn += 8 * b; return true; }
;     __device__ bool map(long L, Unit& u) const {
;         if (L >= nwg) return false;
;         int wgid = (int)L; { const int q = nwg / NXCD, r = nwg % NXCD, xcd = wgid % NXCD, off = wgid / NXCD; wgid = (xcd < r ? xcd * (q + 1) : r * (q + 1) + (xcd - r) * q) + off; }
;         const int nig = WGM * nN, gid = wgid / nig, fm = gid * WGM, gsz = (nM - fm) < WGM ? (nM - fm) : WGM;
;         u.pm = fm + ((wgid % nig) % gsz); u.pn = (wgid % nig) / gsz; return true;
;     }
;     __device__ bool next(int i, Unit& u) const { return map((long)i * G + c, u); }
; template <class Epi, class Sched, bool AREMAP>
; __device__ __forceinline__ void gemm_phase(LAS unsigned char* lds, const Gemm g, const Sched& S, const Epi& E, int wv) {
;     ...
; #pragma unroll
;         for (int a = 0; a < 2; ++a)
; #pragma unroll
;             for (int b = 0; b < 2; ++b)
; #pragma unroll
;                 for (int m = 0; m < 4; ++m)
; #pragma unroll
;                     for (int n = 0; n < 2; ++n) acc[a][b][m][n] = (f32x4){0.f, 0.f, 0.f, 0.f};
.LBB0_616:
	s_add_i32 s41, s41, 1
	s_mul_i32 s8, s41, s36
	s_mul_hi_u32 s9, s41, s52
	s_add_i32 s9, s9, s8
	v_mov_b64_e32 v[4:5], 0
	v_mov_b64_e32 v[66:67], 0
	v_mov_b64_e32 v[68:69], 0
	s_mul_i32 s8, s41, s52
	v_mov_b64_e32 v[10:11], 0
	v_mov_b64_e32 v[12:13], 0
	v_mov_b64_e32 v[74:75], 0
	s_add_u32 s56, s8, s53
	v_mov_b64_e32 v[76:77], 0
	v_mov_b64_e32 v[18:19], 0
	v_mov_b64_e32 v[20:21], 0
	s_addc_u32 s57, s9, s55
	v_mov_b64_e32 v[82:83], 0
	v_mov_b64_e32 v[84:85], 0
	v_mov_b64_e32 v[26:27], 0
	v_mov_b64_e32 v[2:3], 0x15ff
	v_mov_b64_e32 v[28:29], 0
	v_mov_b64_e32 v[90:91], 0
	v_mov_b64_e32 v[92:93], 0
	v_cmp_gt_i64_e64 s[8:9], s[56:57], v[2:3]
	v_mov_b64_e32 v[6:7], 0
	v_mov_b64_e32 v[8:9], 0
	v_mov_b64_e32 v[70:71], 0
	s_and_b64 vcc, exec, s[8:9]
	v_mov_b64_e32 v[72:73], 0
	v_mov_b64_e32 v[14:15], 0
	v_mov_b64_e32 v[16:17], 0
	s_cbranch_vccnz .LBB0_618
	s_ashr_i32 s38, s56, 31
	s_lshr_b32 s38, s38, 29
	s_add_i32 s38, s56, s38
	s_ashr_i32 s39, s38, 3
	s_and_b32 s38, s38, -8
	s_sub_i32 s38, s56, s38
	s_cmp_lt_i32 s38, 0
	s_movk_i32 s33, 0x2c1
	s_cselect_b32 s46, s33, 0x2c0
	s_mul_i32 s38, s46, s38
	s_add_i32 s38, s38, s39
	s_mul_hi_i32 s39, s38, 0x2e8ba2e9
	s_lshr_b32 s46, s39, 31
	s_ashr_i32 s39, s39, 5
	s_add_i32 s39, s39, s46
	s_lshl_b32 s46, s39, 2
	s_sub_i32 s47, 0x80, s46
	s_min_i32 s47, s47, 4
	s_abs_i32 s62, s47
	v_cvt_f32_u32_e32 v2, s62
	s_sub_i32 s66, 0, s62
	s_mulk_i32 s39, 0xb0
	s_sub_i32 s38, s38, s39
	v_rcp_iflag_f32_e32 v2, v2
	s_abs_i32 s39, s38
	s_xor_b32 s63, s38, s47
	s_ashr_i32 s63, s63, 31
	v_mul_f32_e32 v2, 0x4f7ffffe, v2
	v_cvt_u32_f32_e32 v2, v2
	s_nop 0
	v_readfirstlane_b32 s67, v2
	s_mul_i32 s66, s66, s67
	s_mul_hi_u32 s66, s67, s66
	s_add_i32 s67, s67, s66
	s_mul_hi_u32 s66, s39, s67
	s_mul_i32 s67, s66, s62
	s_sub_i32 s39, s39, s67
	s_add_i32 s68, s66, 1
	s_sub_i32 s67, s39, s62
	s_cmp_ge_u32 s39, s62
	s_cselect_b32 s66, s68, s66
	s_cselect_b32 s39, s67, s39
	s_add_i32 s67, s66, 1
	s_cmp_ge_u32 s39, s62
	s_cselect_b32 s39, s67, s66
	s_xor_b32 s39, s39, s63
	s_sub_i32 s62, s39, s63
	s_mul_i32 s39, s62, s47
	s_sub_i32 s38, s38, s39
	s_add_i32 s66, s38, s46
.LBB0_618:
	s_ashr_i32 s67, s66, 31
	v_mov_b64_e32 v[78:79], 0
	v_mov_b64_e32 v[80:81], 0
	v_mov_b64_e32 v[22:23], 0
	s_lshl_b64 s[46:47], s[66:67], 20
	v_mov_b64_e32 v[24:25], 0
	v_mov_b64_e32 v[86:87], 0
	v_mov_b64_e32 v[88:89], 0
	v_mov_b64_e32 v[2:3], 0x1600
	v_mov_b64_e32 v[30:31], 0
	v_mov_b64_e32 v[32:33], 0
	v_mov_b64_e32 v[94:95], 0
	s_add_u32 s68, s65, s46
	v_mov_b64_e32 v[96:97], 0
	v_mov_b64_e32 v[34:35], 0
	v_mov_b64_e32 v[36:37], 0
	v_cmp_lt_i64_e32 vcc, s[56:57], v[2:3]
	v_mov_b64_e32 v[98:99], 0
	v_mov_b64_e32 v[100:101], 0
	v_mov_b64_e32 v[42:43], 0
	s_addc_u32 s69, s72, s47
	v_mov_b64_e32 v[44:45], 0
	v_mov_b64_e32 v[106:107], 0
	v_mov_b64_e32 v[108:109], 0
	s_and_b64 s[46:47], vcc, exec
	v_mov_b64_e32 v[50:51], 0
	v_mov_b64_e32 v[52:53], 0
	v_mov_b64_e32 v[114:115], 0
	s_cselect_b32 s46, s69, s81
	v_mov_b64_e32 v[116:117], 0
	v_mov_b64_e32 v[58:59], 0
	v_mov_b64_e32 v[60:61], 0
	s_cselect_b32 s47, s68, s80
	v_mov_b64_e32 v[122:123], 0
	v_mov_b64_e32 v[124:125], 0
	v_mov_b64_e32 v[38:39], 0
	s_ashr_i32 s63, s62, 31
	v_mov_b64_e32 v[40:41], 0
	v_mov_b64_e32 v[102:103], 0
	v_mov_b64_e32 v[104:105], 0
	s_lshl_b64 s[56:57], s[62:63], 20
	v_mov_b64_e32 v[46:47], 0
	v_mov_b64_e32 v[48:49], 0
	v_mov_b64_e32 v[110:111], 0
	s_add_u32 s56, s73, s56
	v_mov_b64_e32 v[112:113], 0
	v_mov_b64_e32 v[54:55], 0
	v_mov_b64_e32 v[56:57], 0
	s_addc_u32 s57, s74, s57
	v_mov_b64_e32 v[118:119], 0
	v_mov_b64_e32 v[120:121], 0
	v_mov_b64_e32 v[62:63], 0
	s_and_b64 s[96:97], vcc, exec
	v_mov_b64_e32 v[64:65], 0
	v_mov_b64_e32 v[126:127], 0
	v_mov_b64_e32 v[128:129], 0
	s_cselect_b32 s63, s57, s79
	s_cselect_b32 s67, s56, s78
	s_add_u32 s77, s78, 0x100
	s_addc_u32 vcc_lo, s79, 0
	s_add_u32 s78, s80, 0x40080
	v_mov_b64_e32 v[2:3], 0
	s_addc_u32 s79, s81, 0
	s_mov_b32 vcc_hi, -2

;     __device__ bool next(int i, Unit& u) const { const int t = i / 3, b = i - 3 * t; if (!so.map((long)t * so.G + so.c, u)) return false; u.pn += 8 * b; return true; }
;     __device__ bool map(long L, Unit& u) const {
;         if (L >= nwg) return false;
;         int wgid = (int)L; { const int q = nwg / NXCD, r = nwg % NXCD, xcd = wgid % NXCD, off = wgid / NXCD; wgid = (xcd < r ? xcd * (q + 1) : r * (q + 1) + (xcd - r) * q) + off; }
;         const int nig = WGM * nN, gid = wgid / nig, fm = gid * WGM, gsz = (nM - fm) < WGM ? (nM - fm) : WGM;
;         u.pm = fm + ((wgid % nig) % gsz); u.pn = (wgid % nig) / gsz; return true;
;     }
;     __device__ bool next(int i, Unit& u) const { return map((long)i * G + c, u); }
; template <class Epi, class Sched, bool AREMAP>
; __device__ __forceinline__ void gemm_phase(LAS unsigned char* lds, const Gemm g, const Sched& S, const Epi& E, int wv) {
;     ...
; #pragma unroll
;         for (int a = 0; a < 2; ++a)
; #pragma unroll
;             for (int b = 0; b < 2; ++b)
; #pragma unroll
;                 for (int m = 0; m < 4; ++m)
; #pragma unroll
;                     for (int n = 0; n < 2; ++n) acc[a][b][m][n] = (f32x4){0.f, 0.f, 0.f, 0.f};
.LBB0_663:
	s_add_i32 s55, s55, 1
	s_mul_i32 s0, s55, s52
	s_mul_hi_u32 s1, s55, s11
	s_add_i32 s1, s1, s0
	v_mov_b64_e32 v[4:5], 0
	v_mov_b64_e32 v[18:19], 0
	v_mov_b64_e32 v[20:21], 0
	v_mov_b64_e32 v[6:7], 0
	v_mov_b64_e32 v[8:9], 0
	v_mov_b64_e32 v[22:23], 0
	v_mov_b64_e32 v[24:25], 0
	v_mov_b64_e32 v[10:11], 0
	s_mul_i32 s0, s55, s11
	v_mov_b64_e32 v[12:13], 0
	v_mov_b64_e32 v[26:27], 0
	v_mov_b64_e32 v[28:29], 0
	v_mov_b64_e32 v[14:15], 0
	v_mov_b64_e32 v[16:17], 0
	v_mov_b64_e32 v[30:31], 0
	v_mov_b64_e32 v[32:33], 0
	v_mov_b64_e32 v[34:35], 0
	s_add_u32 s4, s0, s12
	v_mov_b64_e32 v[36:37], 0
	v_mov_b64_e32 v[50:51], 0
	v_mov_b64_e32 v[52:53], 0
	v_mov_b64_e32 v[38:39], 0
	v_mov_b64_e32 v[40:41], 0
	v_mov_b64_e32 v[54:55], 0
	v_mov_b64_e32 v[56:57], 0
	v_mov_b64_e32 v[42:43], 0
	s_addc_u32 s5, s1, s53
	v_mov_b64_e32 v[44:45], 0
	v_mov_b64_e32 v[58:59], 0
	v_mov_b64_e32 v[60:61], 0
	v_mov_b64_e32 v[46:47], 0
	v_mov_b64_e32 v[48:49], 0
	v_mov_b64_e32 v[62:63], 0
	v_mov_b64_e32 v[64:65], 0
	v_mov_b64_e32 v[66:67], 0
	v_cmp_gt_i64_e64 s[0:1], s[4:5], v[188:189]
	v_mov_b64_e32 v[68:69], 0
	v_mov_b64_e32 v[82:83], 0
	v_mov_b64_e32 v[84:85], 0
	v_mov_b64_e32 v[70:71], 0
	v_mov_b64_e32 v[72:73], 0
	v_mov_b64_e32 v[86:87], 0
	v_mov_b64_e32 v[88:89], 0
	v_mov_b64_e32 v[74:75], 0
	v_cmp_lt_i64_e64 s[2:3], s[4:5], v[190:191]
	v_mov_b64_e32 v[76:77], 0
	v_mov_b64_e32 v[90:91], 0
	v_mov_b64_e32 v[92:93], 0
	v_mov_b64_e32 v[78:79], 0
	v_mov_b64_e32 v[80:81], 0
	v_mov_b64_e32 v[94:95], 0
	v_mov_b64_e32 v[96:97], 0
	v_mov_b64_e32 v[98:99], 0
	s_and_b64 vcc, exec, s[0:1]
	v_mov_b64_e32 v[100:101], 0
	v_mov_b64_e32 v[114:115], 0
	v_mov_b64_e32 v[116:117], 0
	v_mov_b64_e32 v[102:103], 0
	v_mov_b64_e32 v[104:105], 0
	v_mov_b64_e32 v[118:119], 0
	v_mov_b64_e32 v[120:121], 0
	v_mov_b64_e32 v[106:107], 0
	s_cbranch_vccnz .LBB0_669
	s_ashr_i32 s5, s4, 31
	s_lshr_b32 s5, s5, 29
	s_add_i32 s22, s4, s5
	s_and_b32 s5, s22, -8
	s_sub_i32 s23, s4, s5
	s_cmp_gt_i32 s23, -1
	s_mov_b64 s[4:5], -1
	s_cbranch_scc0 .LBB0_666
	s_lshl_b32 s28, s23, 7
	s_mov_b64 s[4:5], 0

; template <class Epi, class Sched, bool AREMAP>
; __device__ __forceinline__ void gemm_phase(LAS unsigned char* lds, const Gemm g, const Sched& S, const Epi& E, int wv) {
;     ...
;             const char* a2 = last ? nA : cA + (size_t)(t + 2) * kstep; const char* b2 = last ? nB : cB + (size_t)(t + 2) * kstep;
;     ...
; #pragma unroll
;         for (int a = 0; a < 2; ++a)
; #pragma unroll
;             for (int b = 0; b < 2; ++b)
; #pragma unroll
;                 for (int m = 0; m < 4; ++m)
; #pragma unroll
;                     for (int n = 0; n < 2; ++n) acc[a][b][m][n] = (f32x4){0.f, 0.f, 0.f, 0.f};
.LBB0_673:
	s_add_u32 s65, s26, 0x100
	v_mov_b64_e32 v[108:109], 0
	v_mov_b64_e32 v[122:123], 0
	v_mov_b64_e32 v[124:125], 0
	v_mov_b64_e32 v[110:111], 0
	v_mov_b64_e32 v[112:113], 0
	v_mov_b64_e32 v[126:127], 0
	v_mov_b64_e32 v[128:129], 0
	v_mov_b64_e32 v[2:3], 0
	s_addc_u32 s66, s27, 0
	s_mov_b32 s67, -2
